# P4->P5 barrier XCC-local: ret_out pairs re-dealt so a row block's heads are produced on the consuming XCC; XCC leader writes back and bumps a knorm-done counter checked at P6/xattn entry
# speedup vs baseline: 1.0102x; 1.0022x over previous
.LBB0_592:
	v_readlane_b32 s0, v254, 62
	v_readlane_b32 s1, v254, 63
	s_andn2_b64 vcc, exec, s[0:1]
	s_waitcnt lgkmcnt(0)
	v_cndmask_b32_e64 v0, 0, 1, s[0:1]
	v_cmp_ne_u32_e64 s[4:5], 1, v0
	s_barrier
	v_mbcnt_lo_u32_b32 v152, -1, 0
	v_mbcnt_hi_u32_b32 v152, -1, v152
	s_cbranch_vccnz .LBB0_598
	v_lshlrev_b32_e32 v7, 4, v152
	v_readlane_b32 s6, v254, 45
	v_and_b32_e32 v128, 0x70, v7
	v_mov_b32_e32 v129, 0
	v_readlane_b32 s7, v254, 46
	v_and_b32_e32 v0, 0xf0, v7
	v_mov_b32_e32 v1, v129
	v_lshl_add_u64 v[130:131], s[6:7], 0, v[128:129]
	v_readlane_b32 s6, v255, 0
	v_readlane_b32 s7, v255, 1
	v_lshrrev_b32_e32 v10, 1, v152
	v_and_b32_e32 v6, 31, v152
	v_lshl_add_u64 v[132:133], s[6:7], 0, v[0:1]
	v_lshlrev_b32_e32 v0, 1, v152
	v_and_b32_e32 v12, 19, v152
	v_and_b32_e32 v13, 8, v0
	v_and_b32_e32 v14, 4, v10
	v_ashrrev_i32_e32 v153, 5, v152
	v_readlane_b32 s0, v254, 48
	v_or_b32_e32 v134, s42, v6
	v_or3_b32 v0, v14, v12, v13
	s_lshl_b32 s0, s0, 16
	v_lshrrev_b32_e32 v15, 1, v0
	v_lshlrev_b32_e32 v0, 3, v153
	v_add_u32_e32 v1, 1, v134
	s_add_i32 s1, s0, 0
	v_readlane_b32 s2, v254, 52
	v_cvt_f32_ubyte0_e32 v157, v1
	v_ashrrev_i32_e32 v1, 31, v0
	v_readlane_b32 s7, v254, 53
	v_lshl_add_u32 v3, s2, 6, v152
	s_movk_i32 s3, 0x70
	v_bfe_u32 v11, v152, 1, 3
	v_lshl_add_u64 v[4:5], v[0:1], 2, s[8:9]
	s_add_i32 s2, s1, s7
	v_lshlrev_b32_e32 v1, 7, v6
	v_bitop3_b32 v8, v3, s3, v7 bitop3:0x48
	v_lshlrev_b32_e32 v2, 8, v6
	v_add3_u32 v159, s2, v1, v0
	v_lshlrev_b32_e32 v160, 4, v11
	v_ashrrev_i32_e32 v136, 3, v3
	v_ashrrev_i32_e32 v161, 4, v3
	v_add_u32_e32 v1, 0x100, v3
	v_add_u32_e32 v6, 0x200, v3
	v_add_u32_e32 v11, 0x300, v3
	v_lshlrev_b32_e32 v3, 4, v3
	s_movk_i32 s6, 0xff80
	v_and_or_b32 v17, v3, s6, v8
	v_xor_b32_e32 v3, v161, v152
	v_ashrrev_i32_e32 v162, 4, v1
	v_lshlrev_b32_e32 v3, 4, v3
	v_and_b32_e32 v19, 0xf0, v3
	v_xor_b32_e32 v3, v162, v152
	v_lshlrev_b32_e32 v3, 4, v3
	v_ashrrev_i32_e32 v163, 4, v6
	v_and_b32_e32 v21, 0xf0, v3
	v_lshlrev_b32_e32 v3, 4, v6
	v_ashrrev_i32_e32 v140, 3, v6
	v_and_or_b32 v6, v3, s6, v8
	v_xor_b32_e32 v3, v163, v152
	v_lshlrev_b32_e32 v3, 4, v3
	v_ashrrev_i32_e32 v138, 3, v1
	v_ashrrev_i32_e32 v164, 4, v11
	v_lshlrev_b32_e32 v1, 4, v1
	v_and_b32_e32 v23, 0xf0, v3
	v_lshlrev_b32_e32 v3, 4, v11
	v_and_or_b32 v1, v1, s6, v8
	v_and_or_b32 v8, v3, s6, v8
	v_xor_b32_e32 v3, v164, v152
	v_lshlrev_b32_e32 v3, 4, v3
	v_add_u32_e32 v16, 2, v153
	v_and_b32_e32 v24, 0xf0, v3
	v_bitop3_b32 v3, v10, v153, 7 bitop3:0x6c
	v_lshlrev_b32_e32 v25, 4, v3
	v_bitop3_b32 v3, v16, v10, 7 bitop3:0x78
	v_lshlrev_b32_e32 v26, 4, v3
	v_add_u32_e32 v3, 4, v153
	v_bitop3_b32 v27, v3, v10, 7 bitop3:0x78
	v_add_u32_e32 v28, 6, v153
	v_bitop3_b32 v3, v15, v3, 7 bitop3:0x6c
	v_lshlrev_b32_e32 v30, 4, v3
	v_bitop3_b32 v3, v15, v28, 7 bitop3:0x6c
	v_bitop3_b32 v29, v15, v153, 7 bitop3:0x6c
	v_bitop3_b32 v16, v15, v16, 7 bitop3:0x6c
	v_lshlrev_b32_e32 v15, 4, v3
	v_mov_b32_e32 v3, 0x70
	s_movk_i32 s6, 0x50
	v_bitop3_b32 v38, v7, s6, v3 bitop3:0x6c
	s_movk_i32 s6, 0x60
	v_bitop3_b32 v31, v7, 16, v3 bitop3:0x6c
	v_bitop3_b32 v33, v7, 32, v3 bitop3:0x6c
	v_bitop3_b32 v35, v7, 48, v3 bitop3:0x6c
	v_bitop3_b32 v36, v7, 64, v3 bitop3:0x6c
	v_bitop3_b32 v40, v7, s6, v3 bitop3:0x6c
	v_mov_b32_e32 v3, v129
	v_add_u32_e32 v155, s1, v2
	v_lshl_add_u64 v[150:151], v[4:5], 0, v[2:3]
	v_or3_b32 v2, v12, v13, v14
	v_lshl_or_b32 v2, v2, 7, s0
	v_add3_u32 v3, v2, v15, 0
	v_lshl_add_u32 v9, v134, 7, s1
	v_bitop3_b32 v10, v28, v10, 7 bitop3:0x78
	v_lshlrev_b32_e32 v29, 4, v29
	v_lshlrev_b32_e32 v16, 4, v16
	v_add_u32_e32 v165, 0x4000, v3
	v_add3_u32 v3, v2, v30, 0
	s_mov_b32 s61, 0
	v_sub_u32_e32 v154, 0, v0
	v_add_u32_e32 v158, v9, v0
	v_xor_b32_e32 v0, 64, v160
	v_ashrrev_i32_e32 v142, 3, v11
	v_lshl_add_u32 v18, v161, 8, s1
	v_lshl_add_u32 v20, v162, 8, s1
	v_lshl_add_u32 v22, v163, 8, s1
	v_lshl_add_u32 v11, v164, 8, s1
	v_lshlrev_b32_e32 v27, 4, v27
	v_lshlrev_b32_e32 v10, 4, v10
	v_xor_b32_e32 v28, 16, v160
	v_xor_b32_e32 v32, 32, v160
	v_xor_b32_e32 v34, 48, v160
	v_xor_b32_e32 v37, 0x50, v160
	v_xor_b32_e32 v39, 0x60, v160
	v_xor_b32_e32 v41, 0x70, v160
	v_bitop3_b32 v7, v7, s3, v7 bitop3:0xc
	v_add_u32_e32 v166, 0x4000, v3
	v_add3_u32 v3, v2, v16, 0
	v_add3_u32 v2, v2, v29, 0
	v_and_b32_e32 v156, 15, v152
	s_mov_b32 s43, s61
	v_ashrrev_i32_e32 v137, 31, v136
	v_ashrrev_i32_e32 v139, 31, v138
	v_ashrrev_i32_e32 v141, 31, v140
	v_ashrrev_i32_e32 v143, 31, v142
	v_add_u32_e32 v135, -1, v134
	v_add_u32_e32 v145, -3, v134
	v_add_u32_e32 v144, -2, v134
	v_add_u32_e32 v147, -5, v134
	v_add_u32_e32 v146, -4, v134
	v_add_u32_e32 v149, -7, v134
	v_add_u32_e32 v148, -6, v134
	s_add_i32 s3, s7, 0x1000
	v_add_u32_e32 v167, 0x4000, v3
	v_add_u32_e32 v168, 0x4000, v2
	s_mov_b32 s10, 0xc2fc0000
	v_mov_b32_e32 v169, 0x3ecc95a3
	s_movk_i32 s11, 0x1400
	v_add_u32_e32 v170, s1, v17
	v_add_u32_e32 v171, v18, v19
	v_add_u32_e32 v172, s1, v1
	v_add_u32_e32 v173, v20, v21
	v_add_u32_e32 v174, s1, v6
	v_add_u32_e32 v175, v22, v23
	v_add_u32_e32 v176, s1, v8
	v_add_u32_e32 v177, v11, v24
	v_add_u32_e32 v178, v9, v25
	v_add_u32_e32 v179, v9, v26
	v_add_u32_e32 v180, v9, v27
	v_add_u32_e32 v181, v9, v10
	s_mov_b32 s20, 0x5040100
	s_mov_b64 s[62:63], 0x2040
	s_mov_b64 s[64:65], 0x2080
	s_mov_b64 s[66:67], 0x20c0
	v_add_u32_e32 v182, v158, v28
	v_add_u32_e32 v183, v158, v32
	v_add_u32_e32 v184, v158, v34
	v_add_u32_e32 v185, v158, v0
	v_add_u32_e32 v186, v158, v37
	v_add_u32_e32 v187, v158, v39
	v_add_u32_e32 v188, v158, v41
	v_mov_b32_e32 v189, 0x358637bd
	s_mov_b32 s21, 0x800000
	v_add_u32_e32 v190, v159, v31
	v_add_u32_e32 v191, v159, v33
	v_add_u32_e32 v192, v159, v35
	v_add_u32_e32 v193, v159, v36
	v_add_u32_e32 v194, v159, v38
	v_add_u32_e32 v195, v159, v40
	v_add_u32_e32 v196, v159, v7
	v_mov_b32_e32 v197, 0x42800000
	v_mov_b32_e32 v198, 0x7fc00000
	v_mov_b32_e32 v199, 0xff800000
	v_not_b32_e32 v200, 63
	s_mov_b32 s33, s70
	s_mov_b32 s101, s78
	s_cmp_lg_u32 s98, 0
	s_cbranch_scc0 .Lro_nodeal
	s_and_b32 s99, s70, 7
	s_lshr_b32 s100, s70, 3
	s_lshr_b32 s33, s99, 2
	s_lshl_b32 s33, s33, 3
	s_lshr_b32 s101, s100, 2
	s_or_b32 s33, s33, s101
	s_lshl_b32 s33, s33, 5
	s_and_b32 s99, s99, 3
	s_lshl_b32 s99, s99, 3
	s_or_b32 s33, s33, s99
	s_and_b32 s100, s100, 3
	s_lshl_b32 s100, s100, 1
	s_or_b32 s33, s33, s100
	s_mov_b32 s101, 1
.Lro_nodeal:
.LBB0_594:
	s_lshl_b32 s0, s33, 1
	v_readlane_b32 s1, v254, 48
	s_add_i32 s82, s0, s1
	s_bfe_u32 s6, s82, 0x30006
	v_cvt_f32_ubyte0_e32 v0, s6
	v_sub_f32_e32 v0, 0xc0a00000, v0
	s_ashr_i32 s0, s82, 9
	v_cmp_gt_f32_e32 vcc, s10, v0
	s_ashr_i32 s1, s0, 31
	s_lshl_b64 s[68:69], s[0:1], 13
	v_cndmask_b32_e32 v1, 0, v197, vcc
	s_lshl_b32 s0, s82, 7
	v_add_f32_e32 v0, v0, v1
	s_and_b32 s0, s0, 0x1f80
	v_exp_f32_e32 v0, v0
	s_or_b32 s68, s68, s0
	s_and_b64 s[0:1], vcc, exec
	s_cselect_b32 s0, 0xffffffc0, 0
	v_ldexp_f32 v64, v0, s0
	v_sub_f32_e32 v2, 1.0, v64
	v_add_f32_e32 v0, -1.0, v2
	v_sub_f32_e32 v1, v0, v2
	v_add_f32_e32 v1, 1.0, v1
	v_sub_f32_e64 v0, -v64, v0
	v_add_f32_e32 v3, v0, v1
	v_frexp_mant_f32_e32 v4, v2
	v_cvt_f64_f32_e32 v[0:1], v2
	s_mov_b32 s0, 0x3f2aaaab
	v_frexp_exp_i32_f64_e32 v0, v[0:1]
	v_cmp_gt_f32_e32 vcc, s0, v4
	s_lshl_b32 s40, s6, 6
	s_lshl_b32 s60, s6, 7
	v_subbrev_co_u32_e32 v65, vcc, 0, v0, vcc
	v_sub_u32_e32 v0, 0, v65
	v_ldexp_f32 v1, v2, v0
	v_add_f32_e32 v2, -1.0, v1
	v_add_f32_e32 v5, 1.0, v1
	v_ldexp_f32 v0, v3, v0
	v_add_f32_e32 v3, 1.0, v2
	v_add_f32_e32 v6, -1.0, v5
	v_sub_f32_e32 v3, v1, v3
	v_sub_f32_e32 v1, v1, v6
	v_add_f32_e32 v3, v0, v3
	v_add_f32_e32 v0, v0, v1
	v_add_f32_e32 v1, v5, v0
	v_rcp_f32_e32 v66, v1
	v_add_f32_e32 v4, v2, v3
	v_sub_f32_e32 v2, v4, v2
	v_sub_f32_e32 v2, v3, v2
	v_sub_f32_e32 v3, v1, v5
	v_mul_f32_e32 v67, v4, v66
	v_sub_f32_e32 v0, v0, v3
	v_mul_f32_e32 v3, v1, v67
	v_fma_f32 v5, v67, v1, -v3
	v_fmac_f32_e32 v5, v67, v0
	v_add_f32_e32 v6, v3, v5
	v_sub_f32_e32 v68, v4, v6
	v_sub_f32_e32 v4, v4, v68
	v_sub_f32_e32 v3, v6, v3
	v_sub_f32_e32 v4, v4, v6
	v_add_f32_e32 v2, v2, v4
	v_sub_f32_e32 v3, v3, v5
	v_add_f32_e32 v69, v3, v2
	v_add_f32_e32 v70, v68, v69
	s_or_b32 s6, s40, 0x200
	v_mul_f32_e32 v71, v66, v70
	v_add_u32_e32 v8, s6, v161
	v_mul_f32_e32 v72, v1, v71
	v_ashrrev_i32_e32 v9, 31, v8
	v_fma_f32 v73, v71, v1, -v72
	v_lshl_add_u64 v[60:61], s[68:69], 1, v[132:133]
	v_lshlrev_b64 v[8:9], 15, v[8:9]
	v_add_u32_e32 v26, s6, v162
	v_add_u32_e32 v40, s6, v163
	v_fmac_f32_e32 v73, v71, v0
	v_lshl_add_u64 v[44:45], v[130:131], 0, s[60:61]
	v_lshl_add_u64 v[0:1], s[68:69], 0, v[136:137]
	v_lshl_add_u64 v[24:25], v[60:61], 0, v[8:9]
	v_lshl_add_u64 v[8:9], s[68:69], 0, v[138:139]
	v_ashrrev_i32_e32 v27, 31, v26
	v_lshl_add_u64 v[32:33], s[68:69], 0, v[140:141]
	v_ashrrev_i32_e32 v41, 31, v40
	v_lshl_add_u64 v[46:47], s[68:69], 0, v[142:143]
	v_mad_u64_u32 v[16:17], s[0:1], v0, s11, v[44:45]
	v_mad_u64_u32 v[20:21], s[0:1], v8, s11, v[44:45]
	v_lshlrev_b64 v[26:27], 15, v[26:27]
	v_mad_u64_u32 v[52:53], s[0:1], v32, s11, v[44:45]
	v_lshlrev_b64 v[40:41], 15, v[40:41]
	v_mad_u64_u32 v[56:57], s[0:1], v46, s11, v[44:45]
	v_mad_i32_i24 v17, v1, s11, v17
	v_mad_i32_i24 v21, v9, s11, v21
	v_lshl_add_u64 v[28:29], v[60:61], 0, v[26:27]
	v_mad_i32_i24 v53, v33, s11, v53
	v_lshl_add_u64 v[40:41], v[60:61], 0, v[40:41]
	v_mad_i32_i24 v57, v47, s11, v57
	s_barrier
	global_load_dwordx4 v[0:3], v[16:17], off offset:1024 nt
	global_load_dwordx4 v[4:7], v[16:17], off offset:2048 nt
	global_load_dwordx4 v[8:11], v[20:21], off nt
	global_load_dwordx4 v[12:15], v[20:21], off offset:1024 nt
	s_nop 0
	global_load_dwordx4 v[16:19], v[16:17], off nt
	s_nop 0
	global_load_dwordx4 v[20:23], v[20:21], off offset:2048 nt
	s_nop 0
	global_load_dwordx4 v[24:27], v[24:25], off nt
	s_nop 0
	global_load_dwordx4 v[28:31], v[28:29], off nt
	s_nop 0
	global_load_dwordx4 v[32:35], v[52:53], off offset:1024 nt
	global_load_dwordx4 v[36:39], v[52:53], off offset:2048 nt
	v_add_u32_e32 v62, s6, v164
	global_load_dwordx4 v[40:43], v[40:41], off nt
	s_nop 0
	global_load_dwordx4 v[44:47], v[56:57], off nt
	global_load_dwordx4 v[48:51], v[56:57], off offset:1024 nt
	s_nop 0
	global_load_dwordx4 v[52:55], v[52:53], off nt
	s_nop 0
	global_load_dwordx4 v[56:59], v[56:57], off offset:2048 nt
	v_ashrrev_i32_e32 v63, 31, v62
	v_lshlrev_b64 v[62:63], 15, v[62:63]
	v_lshl_add_u64 v[60:61], v[60:61], 0, v[62:63]
	global_load_dwordx4 v[60:63], v[60:61], off nt
	v_sub_f32_e32 v68, v68, v70
	v_add_f32_e32 v68, v69, v68
	v_add_f32_e32 v69, v72, v73
	v_sub_f32_e32 v74, v70, v69
	v_sub_f32_e32 v70, v70, v74
	v_sub_f32_e32 v72, v69, v72
	v_sub_f32_e32 v69, v70, v69
	v_add_f32_e32 v68, v68, v69
	v_sub_f32_e32 v69, v72, v73
	v_add_f32_e32 v68, v69, v68
	v_add_f32_e32 v68, v74, v68
	v_cvt_f32_i32_e32 v65, v65
	v_mul_f32_e32 v66, v66, v68
	v_add_f32_e32 v68, v67, v71
	v_sub_f32_e32 v67, v68, v67
	v_sub_f32_e32 v67, v71, v67
	v_add_f32_e32 v66, v67, v66
	v_mul_f32_e32 v71, 0x3f317218, v65
	s_mov_b32 s0, 0x3f317218
	v_add_f32_e32 v67, v68, v66
	v_fma_f32 v72, v65, s0, -v71
	v_mul_f32_e32 v69, v67, v67
	v_fmac_f32_e32 v72, 0xb102e308, v65
	v_sub_f32_e32 v65, v67, v68
	v_fmamk_f32 v70, v69, 0x3e9b6dac, v169
	v_sub_f32_e32 v65, v66, v65
	v_add_f32_e32 v66, v71, v72
	v_fmaak_f32 v70, v69, v70, 0x3f2aaada
	v_sub_f32_e32 v68, v66, v71
	v_ldexp_f32 v71, v67, 1
	v_mul_f32_e32 v67, v67, v69
	v_mul_f32_e32 v67, v67, v70
	v_add_f32_e32 v69, v71, v67
	v_sub_f32_e32 v70, v69, v71
	v_ldexp_f32 v65, v65, 1
	v_sub_f32_e32 v67, v67, v70
	v_add_f32_e32 v65, v65, v67
	v_add_f32_e32 v67, v69, v65
	v_sub_f32_e32 v69, v67, v69
	v_sub_f32_e32 v65, v65, v69
	v_add_f32_e32 v69, v66, v67
	v_sub_f32_e32 v70, v69, v66
	v_sub_f32_e32 v71, v69, v70
	v_sub_f32_e32 v68, v72, v68
	v_sub_f32_e32 v66, v66, v71
	v_sub_f32_e32 v67, v67, v70
	v_add_f32_e32 v66, v67, v66
	v_add_f32_e32 v67, v68, v65
	v_sub_f32_e32 v70, v67, v68
	v_sub_f32_e32 v71, v67, v70
	v_add_f32_e32 v66, v67, v66
	v_sub_f32_e32 v68, v68, v71
	v_sub_f32_e32 v65, v65, v70
	v_add_f32_e32 v67, v69, v66
	v_add_f32_e32 v65, v65, v68
	v_sub_f32_e32 v68, v67, v69
	v_sub_f32_e32 v66, v66, v68
	v_add_f32_e32 v65, v65, v66
	v_add_f32_e32 v65, v67, v65
	v_cmp_nlt_f32_e32 vcc, 1.0, v64
	s_mov_b32 s0, 0x33800000
	s_waitcnt vmcnt(0)
	ds_write_b128 v170, v[16:19]
	ds_write_b128 v170, v[0:3] offset:16384
	ds_write_b128 v170, v[4:7] offset:32768
	ds_write_b128 v171, v[24:27] offset:49152
	ds_write_b128 v172, v[8:11]
	ds_write_b128 v172, v[12:15] offset:16384
	ds_write_b128 v172, v[20:23] offset:32768
	ds_write_b128 v173, v[28:31] offset:49152
	ds_write_b128 v174, v[52:55]
	ds_write_b128 v174, v[32:35] offset:16384
	ds_write_b128 v174, v[36:39] offset:32768
	ds_write_b128 v175, v[40:43] offset:49152
	ds_write_b128 v176, v[44:47]
	ds_write_b128 v176, v[48:51] offset:16384
	ds_write_b128 v176, v[56:59] offset:32768
	ds_write_b128 v177, v[60:63] offset:49152
	v_cndmask_b32_e32 v65, v198, v65, vcc
	v_cmp_neq_f32_e32 vcc, 1.0, v64
	s_waitcnt lgkmcnt(0)
	s_barrier
	v_cndmask_b32_e32 v65, v199, v65, vcc
	v_cmp_gt_f32_e32 vcc, s0, v64
	v_mov_b32_e32 v48, v154
	s_nop 0
	v_cndmask_b32_e64 v80, v65, -v64, vcc
	ds_read_b128 v[76:79], v178
	ds_read_b128 v[72:75], v179
	ds_read_b128 v[68:71], v180
	ds_read_b128 v[64:67], v181
	v_mul_f32_e32 v201, 0x3fb8aa3b, v80
	v_mov_b32_e32 v49, v153
	s_mov_b32 s41, 0
	v_mov_b32_e32 v16, 0
	v_mov_b32_e32 v17, v129
	v_mov_b32_e32 v18, v129
	v_mov_b32_e32 v19, v129
	v_mov_b32_e32 v20, v129
	v_mov_b32_e32 v21, v129
	v_mov_b32_e32 v22, v129
	v_mov_b32_e32 v23, v129
	v_mov_b32_e32 v24, v129
	v_mov_b32_e32 v25, v129
	v_mov_b32_e32 v26, v129
	v_mov_b32_e32 v27, v129
	v_mov_b32_e32 v28, v129
	v_mov_b32_e32 v29, v129
	v_mov_b32_e32 v30, v129
	v_mov_b32_e32 v31, v129
	v_mov_b32_e32 v0, 0
	v_mov_b32_e32 v1, v129
	v_mov_b32_e32 v2, v129
	v_mov_b32_e32 v3, v129
	v_mov_b32_e32 v4, v129
	v_mov_b32_e32 v5, v129
	v_mov_b32_e32 v6, v129
	v_mov_b32_e32 v7, v129
	v_mov_b32_e32 v8, v129
	v_mov_b32_e32 v9, v129
	v_mov_b32_e32 v10, v129
	v_mov_b32_e32 v11, v129
	v_mov_b32_e32 v12, v129
	v_mov_b32_e32 v13, v129
	v_mov_b32_e32 v14, v129
	v_mov_b32_e32 v15, v129
	s_ashr_i32 s83, s82, 31
	s_lshl_b64 s[0:1], s[82:83], 14
	v_lshl_add_u64 v[244:245], v[150:151], 0, s[0:1]
	s_mov_b64 s[0:1], 0x2000
	global_load_dwordx4 v[224:227], v[244:245], off nt
	global_load_dwordx4 v[228:231], v[244:245], off offset:16 nt
	v_lshl_add_u64 v[246:247], v[244:245], 0, s[0:1]
	global_load_dwordx4 v[232:235], v[246:247], off nt
	global_load_dwordx4 v[236:239], v[246:247], off offset:16 nt
	global_load_dwordx4 v[100:103], v[244:245], off offset:64 nt
	global_load_dwordx4 v[88:91], v[244:245], off offset:80 nt
	global_load_dwordx4 v[104:107], v[246:247], off offset:64 nt
	v_lshl_add_u64 v[248:249], v[244:245], 0, s[62:63]
	global_load_dwordx4 v[108:111], v[248:249], off offset:16 nt
	global_load_dwordx4 v[92:95], v[244:245], off offset:128 nt
	global_load_dwordx4 v[240:243], v[244:245], off offset:144 nt
	global_load_dwordx4 v[112:115], v[246:247], off offset:128 nt
	v_lshl_add_u64 v[250:251], v[244:245], 0, s[64:65]
	global_load_dwordx4 v[116:119], v[250:251], off offset:16 nt
	global_load_dwordx4 v[96:99], v[244:245], off offset:192 nt
	global_load_dwordx4 v[84:87], v[244:245], off offset:208 nt
	global_load_dwordx4 v[120:123], v[246:247], off offset:192 nt
	v_lshl_add_u64 v[248:249], v[244:245], 0, s[66:67]
	global_load_dwordx4 v[124:127], v[248:249], off offset:16 nt
.LBB0_595:
	v_add_u32_e32 v32, s41, v168
	ds_read_b128 v[32:35], v32
	v_add_u32_e32 v50, s41, v167
	ds_read_b128 v[50:53], v50
	s_waitcnt lgkmcnt(1)
	v_mfma_f32_32x32x16_bf16 v[32:47], v[32:35], v[76:79], 0
	s_waitcnt lgkmcnt(0)
	v_mfma_f32_32x32x16_bf16 v[32:47], v[50:53], v[72:75], v[32:47]
	v_add_u32_e32 v50, s41, v166
	ds_read_b128 v[50:53], v50
	s_waitcnt lgkmcnt(0)
	v_mfma_f32_32x32x16_bf16 v[32:47], v[50:53], v[68:71], v[32:47]
	v_add_u32_e32 v50, s41, v165
	ds_read_b128 v[50:53], v50
	s_addk_i32 s41, 0x1000
	s_cmp_eq_u32 s3, s41
	s_waitcnt lgkmcnt(0)
	v_mfma_f32_32x32x16_bf16 v[32:47], v[50:53], v[64:67], v[32:47]
	v_add_u32_e32 v51, v48, v135
	v_add_u32_e32 v52, v48, v134
	v_cvt_f32_u32_e32 v50, v52
	v_cmp_lt_i32_e32 vcc, -1, v51
	v_cvt_f32_u32_e32 v51, v51
	v_cmp_lt_i32_e64 s[0:1], -1, v52
	v_mul_f32_e32 v50, v201, v50
	v_exp_f32_e32 v50, v50
	v_mul_f32_e32 v51, v201, v51
	v_exp_f32_e32 v51, v51
	v_add_u32_e32 v52, v48, v144
	v_cmp_lt_i32_e64 s[8:9], -1, v52
	v_pk_mul_f32 v[32:33], v[50:51], v[32:33]
	v_add_u32_e32 v51, v48, v145
	v_cvt_f32_u32_e32 v50, v52
	v_cmp_lt_i32_e64 s[6:7], -1, v51
	v_cvt_f32_u32_e32 v51, v51
	v_add_u32_e32 v52, v48, v146
	v_mul_f32_e32 v50, v201, v50
	v_exp_f32_e32 v50, v50
	v_mul_f32_e32 v51, v201, v51
	v_exp_f32_e32 v51, v51
	v_cmp_lt_i32_e64 s[14:15], -1, v52
	v_cvt_pk_bf16_f32 v32, v32, v33
	v_cndmask_b32_e64 v33, 0, v32, s[0:1]
	v_pk_mul_f32 v[34:35], v[50:51], v[34:35]
	v_add_u32_e32 v51, v48, v147
	v_cvt_f32_u32_e32 v50, v52
	v_cmp_lt_i32_e64 s[12:13], -1, v51
	v_cvt_f32_u32_e32 v51, v51
	v_add_u32_e32 v52, v48, v148
	v_mul_f32_e32 v50, v201, v50
	v_exp_f32_e32 v50, v50
	v_mul_f32_e32 v51, v201, v51
	v_exp_f32_e32 v51, v51
	v_cmp_lt_i32_e64 s[18:19], -1, v52
	v_lshrrev_b32_e32 v32, 16, v32
	v_cndmask_b32_e32 v32, 0, v32, vcc
	v_pk_mul_f32 v[50:51], v[50:51], v[36:37]
	v_add_u32_e32 v37, v48, v149
	v_cvt_f32_u32_e32 v36, v52
	v_cmp_lt_i32_e64 s[16:17], -1, v37
	v_cvt_f32_u32_e32 v37, v37
	v_mul_f32_e32 v36, v201, v36
	v_exp_f32_e32 v36, v36
	v_mul_f32_e32 v37, v201, v37
	v_exp_f32_e32 v37, v37
	s_nop 0
	v_pk_mul_f32 v[52:53], v[36:37], v[38:39]
	v_add_u32_e32 v38, -16, v48
	v_add_u32_e32 v37, v38, v135
	v_add_u32_e32 v39, v38, v134
	v_cvt_f32_u32_e32 v36, v39
	v_cmp_lt_i32_e64 s[22:23], -1, v37
	v_cvt_f32_u32_e32 v37, v37
	v_cmp_lt_i32_e64 s[24:25], -1, v39
	v_mul_f32_e32 v36, v201, v36
	v_exp_f32_e32 v36, v36
	v_mul_f32_e32 v37, v201, v37
	v_exp_f32_e32 v37, v37
	v_add_u32_e32 v39, v38, v144
	v_cmp_lt_i32_e64 s[28:29], -1, v39
	v_subrev_u32_e32 v48, 32, v48
	v_pk_mul_f32 v[40:41], v[36:37], v[40:41]
	v_add_u32_e32 v37, v38, v145
	v_cvt_f32_u32_e32 v36, v39
	v_cmp_lt_i32_e64 s[26:27], -1, v37
	v_cvt_f32_u32_e32 v37, v37
	v_add_u32_e32 v39, v38, v146
	v_mul_f32_e32 v36, v201, v36
	v_exp_f32_e32 v36, v36
	v_mul_f32_e32 v37, v201, v37
	v_exp_f32_e32 v37, v37
	v_cmp_lt_i32_e64 s[34:35], -1, v39
	v_pk_mul_f32 v[42:43], v[36:37], v[42:43]
	v_add_u32_e32 v37, v38, v147
	v_cvt_f32_u32_e32 v36, v39
	v_cmp_lt_i32_e64 s[30:31], -1, v37
	v_cvt_f32_u32_e32 v37, v37
	v_mul_f32_e32 v36, v201, v36
	v_exp_f32_e32 v36, v36
	v_mul_f32_e32 v37, v201, v37
	v_exp_f32_e32 v37, v37
	s_nop 0
	v_pk_mul_f32 v[44:45], v[36:37], v[44:45]
	v_add_u32_e32 v37, v38, v149
	v_add_u32_e32 v38, v38, v148
	v_cvt_f32_u32_e32 v36, v38
	v_cmp_lt_i32_e64 s[36:37], -1, v37
	v_cvt_f32_u32_e32 v37, v37
	v_cmp_lt_i32_e64 s[38:39], -1, v38
	v_mul_f32_e32 v36, v201, v36
	v_exp_f32_e32 v36, v36
	v_mul_f32_e32 v37, v201, v37
	v_exp_f32_e32 v37, v37
	s_nop 0
	v_pk_mul_f32 v[46:47], v[36:37], v[46:47]
	v_perm_b32 v36, v32, v33, s20
	v_cvt_pk_bf16_f32 v32, v34, v35
	v_cndmask_b32_e64 v33, 0, v32, s[8:9]
	v_lshrrev_b32_e32 v32, 16, v32
	v_cndmask_b32_e64 v32, 0, v32, s[6:7]
	v_perm_b32 v37, v32, v33, s20
	v_cvt_pk_bf16_f32 v32, v50, v51
	v_cndmask_b32_e64 v33, 0, v32, s[14:15]
	v_lshrrev_b32_e32 v32, 16, v32
	v_cndmask_b32_e64 v32, 0, v32, s[12:13]
	v_perm_b32 v38, v32, v33, s20
	v_cvt_pk_bf16_f32 v32, v52, v53
	v_cndmask_b32_e64 v33, 0, v32, s[18:19]
	v_lshrrev_b32_e32 v32, 16, v32
	v_cndmask_b32_e64 v32, 0, v32, s[16:17]
	v_perm_b32 v39, v32, v33, s20
	v_cvt_pk_bf16_f32 v32, v40, v41
	v_cndmask_b32_e64 v33, 0, v32, s[24:25]
	v_lshrrev_b32_e32 v32, 16, v32
	v_cndmask_b32_e64 v32, 0, v32, s[22:23]
	v_perm_b32 v32, v32, v33, s20
	v_cvt_pk_bf16_f32 v33, v42, v43
	v_cndmask_b32_e64 v34, 0, v33, s[28:29]
	v_lshrrev_b32_e32 v33, 16, v33
	v_cndmask_b32_e64 v33, 0, v33, s[26:27]
	v_perm_b32 v33, v33, v34, s20
	v_cvt_pk_bf16_f32 v34, v44, v45
	v_cndmask_b32_e64 v35, 0, v34, s[34:35]
	v_lshrrev_b32_e32 v34, 16, v34
	v_cndmask_b32_e64 v34, 0, v34, s[30:31]
	v_perm_b32 v34, v34, v35, s20
	v_cvt_pk_bf16_f32 v35, v46, v47
	v_cndmask_b32_e64 v40, 0, v35, s[38:39]
	v_lshrrev_b32_e32 v35, 16, v35
	v_cndmask_b32_e64 v35, 0, v35, s[36:37]
	v_perm_b32 v35, v35, v40, s20
	v_xor_b32_e32 v40, v49, v156
	v_add_u32_e32 v41, 2, v49
	v_lshl_add_u32 v45, v40, 4, v155
	v_xor_b32_e32 v44, v41, v156
	ds_read_b128 v[40:43], v45 offset:49152
	v_lshl_add_u32 v44, v44, 4, v155
	s_waitcnt lgkmcnt(0)
	v_mfma_f32_32x32x16_bf16 v[16:31], v[40:43], v[36:39], v[16:31]
	ds_read_b128 v[40:43], v44 offset:49152
	v_add_u32_e32 v49, 4, v49
	s_waitcnt lgkmcnt(0)
	v_mfma_f32_32x32x16_bf16 v[16:31], v[40:43], v[32:35], v[16:31]
	ds_read_b128 v[40:43], v45 offset:57344
	s_waitcnt lgkmcnt(0)
	v_mfma_f32_32x32x16_bf16 v[0:15], v[40:43], v[36:39], v[0:15]
	ds_read_b128 v[36:39], v44 offset:57344
	s_waitcnt lgkmcnt(0)
	v_mfma_f32_32x32x16_bf16 v[0:15], v[36:39], v[32:35], v[0:15]
	s_cbranch_scc0 .LBB0_595
	s_nop 7
	v_mul_f32_e32 v48, v201, v157
	v_add_u32_e32 v49, v158, v160
	v_cmp_gt_f32_e32 vcc, s10, v48
	ds_read_b64 v[202:203], v185 offset:32768
	ds_read_b64 v[204:205], v186 offset:32768
	ds_read_b64 v[206:207], v187 offset:32768
	ds_read_b64 v[208:209], v188 offset:32768
	ds_read_b64 v[210:211], v49 offset:32768
	ds_read_b64 v[212:213], v182 offset:32768
	ds_read_b64 v[214:215], v183 offset:32768
	ds_read_b64 v[216:217], v184 offset:32768
	v_cndmask_b32_e32 v222, 0, v200, vcc
	s_waitcnt lgkmcnt(3)
	v_lshlrev_b32_e32 v220, 16, v210
	v_and_b32_e32 v221, 0xffff0000, v210
	v_lshlrev_b32_e32 v218, 16, v202
	v_and_b32_e32 v219, 0xffff0000, v202
	s_or_b64 s[0:1], s[68:69], s[42:43]
	s_lshl_b64 s[0:1], s[0:1], 11
	v_readlane_b32 s6, v255, 4
	s_add_u32 s0, s6, s0
	v_readlane_b32 s6, v255, 5
	s_addc_u32 s1, s6, s1
	s_lshl_b32 s6, s40, 1
	s_add_u32 s0, s0, s6
	s_addc_u32 s1, s1, 0
	s_add_i32 s33, s33, s101
	s_cmp_lg_u32 s98, 0
	s_cselect_b32 s101, 0x400, s78
	s_cmpk_gt_i32 s33, 0x1ff
	s_waitcnt vmcnt(15)
	v_cvt_pk_bf16_f32 v32, v224, v225
	v_cvt_pk_bf16_f32 v33, v226, v227
	s_waitcnt vmcnt(14)
	v_cvt_pk_bf16_f32 v34, v228, v229
	v_cvt_pk_bf16_f32 v35, v230, v231
	s_waitcnt vmcnt(12)
	v_cvt_pk_bf16_f32 v38, v236, v237
	v_cvt_pk_bf16_f32 v36, v232, v233
	v_cvt_pk_bf16_f32 v37, v234, v235
	v_cvt_pk_bf16_f32 v39, v238, v239
	v_mfma_f32_32x32x16_bf16 v[48:63], v[32:35], v[76:79], 0
	v_cndmask_b32_e32 v32, 0, v197, vcc
	v_fmac_f32_e32 v32, v201, v157
	v_exp_f32_e32 v201, v32
	s_waitcnt vmcnt(11)
	v_cvt_pk_bf16_f32 v100, v100, v101
	v_cvt_pk_bf16_f32 v101, v102, v103
	s_waitcnt vmcnt(10)
	v_cvt_pk_bf16_f32 v102, v88, v89
	v_cvt_pk_bf16_f32 v103, v90, v91
	v_mfma_f32_32x32x16_bf16 v[32:47], v[36:39], v[76:79], 0
	s_waitcnt vmcnt(9)
	v_cvt_pk_bf16_f32 v76, v104, v105
	v_cvt_pk_bf16_f32 v77, v106, v107
	s_waitcnt vmcnt(8)
	v_cvt_pk_bf16_f32 v78, v108, v109
	v_cvt_pk_bf16_f32 v79, v110, v111
	s_waitcnt vmcnt(7)
	v_cvt_pk_bf16_f32 v88, v92, v93
	v_cvt_pk_bf16_f32 v89, v94, v95
	s_waitcnt vmcnt(6)
	v_cvt_pk_bf16_f32 v90, v240, v241
	v_mfma_f32_32x32x16_bf16 v[48:63], v[100:103], v[72:75], v[48:63]
	v_cvt_pk_bf16_f32 v91, v242, v243
	v_lshlrev_b32_e32 v100, 16, v211
	v_and_b32_e32 v101, 0xffff0000, v211
	s_waitcnt lgkmcnt(2)
	v_lshlrev_b32_e32 v80, 16, v212
	v_and_b32_e32 v81, 0xffff0000, v212
	v_lshlrev_b32_e32 v82, 16, v213
	v_and_b32_e32 v83, 0xffff0000, v213
	v_mfma_f32_32x32x16_bf16 v[32:47], v[76:79], v[72:75], v[32:47]
	s_waitcnt vmcnt(5)
	v_cvt_pk_bf16_f32 v72, v112, v113
	v_cvt_pk_bf16_f32 v73, v114, v115
	s_waitcnt vmcnt(4)
	v_cvt_pk_bf16_f32 v74, v116, v117
	v_cvt_pk_bf16_f32 v75, v118, v119
	s_waitcnt vmcnt(3)
	v_cvt_pk_bf16_f32 v76, v96, v97
	v_cvt_pk_bf16_f32 v77, v98, v99
	s_waitcnt vmcnt(2)
	v_cvt_pk_bf16_f32 v78, v84, v85
	v_mfma_f32_32x32x16_bf16 v[48:63], v[88:91], v[68:71], v[48:63]
	v_cvt_pk_bf16_f32 v79, v86, v87
	s_waitcnt lgkmcnt(1)
	v_lshlrev_b32_e32 v88, 16, v214
	v_and_b32_e32 v89, 0xffff0000, v214
	v_mfma_f32_32x32x16_bf16 v[32:47], v[72:75], v[68:71], v[32:47]
	s_waitcnt vmcnt(1)
	v_cvt_pk_bf16_f32 v68, v120, v121
	v_cvt_pk_bf16_f32 v69, v122, v123
	s_waitcnt vmcnt(0)
	v_cvt_pk_bf16_f32 v70, v124, v125
	v_cvt_pk_bf16_f32 v71, v126, v127
	v_lshlrev_b32_e32 v72, 16, v215
	v_and_b32_e32 v73, 0xffff0000, v215
	s_waitcnt lgkmcnt(0)
	v_lshlrev_b32_e32 v74, 16, v216
	v_mfma_f32_32x32x16_bf16 v[48:63], v[76:79], v[64:67], v[48:63]
	v_ldexp_f32 v78, v201, v222
	v_and_b32_e32 v75, 0xffff0000, v216
	v_lshlrev_b32_e32 v76, 16, v217
	v_and_b32_e32 v77, 0xffff0000, v217
	v_mfma_f32_32x32x16_bf16 v[32:47], v[68:71], v[64:67], v[32:47]
	s_nop 6
	v_fma_f32 v16, v78, v48, v16
	v_fma_f32 v17, v78, v49, v17
	v_fma_f32 v18, v78, v50, v18
	v_fma_f32 v19, v78, v51, v19
	v_mul_f32_e32 v48, v19, v19
	v_pk_fma_f32 v[20:21], v[78:79], v[52:53], v[20:21] op_sel_hi:[0,1,1]
	v_mul_f32_e32 v50, v21, v21
	v_pk_fma_f32 v[22:23], v[78:79], v[54:55], v[22:23] op_sel_hi:[0,1,1]
	v_mul_f32_e32 v52, v23, v23
	v_pk_fma_f32 v[14:15], v[78:79], v[46:47], v[14:15] op_sel_hi:[0,1,1]
	v_mul_f32_e32 v46, v17, v17
	v_pk_fma_f32 v[0:1], v[78:79], v[32:33], v[0:1] op_sel_hi:[0,1,1]
	v_pk_fma_f32 v[32:33], v[16:17], v[16:17], v[46:47] op_sel_hi:[1,1,0]
	v_pk_fma_f32 v[24:25], v[78:79], v[56:57], v[24:25] op_sel_hi:[0,1,1]
	v_pk_fma_f32 v[32:33], v[18:19], v[18:19], v[32:33]
	v_mul_f32_e32 v54, v25, v25
	v_pk_add_f32 v[32:33], v[48:49], v[32:33] op_sel_hi:[0,1]
	v_pk_fma_f32 v[32:33], v[20:21], v[20:21], v[32:33]
	v_pk_fma_f32 v[26:27], v[78:79], v[58:59], v[26:27] op_sel_hi:[0,1,1]
	v_pk_add_f32 v[32:33], v[50:51], v[32:33] op_sel_hi:[0,1]
	v_pk_fma_f32 v[32:33], v[22:23], v[22:23], v[32:33]
	v_mul_f32_e32 v56, v27, v27
	v_pk_add_f32 v[32:33], v[52:53], v[32:33] op_sel_hi:[0,1]
	v_pk_fma_f32 v[32:33], v[24:25], v[24:25], v[32:33]
	v_pk_fma_f32 v[28:29], v[78:79], v[60:61], v[28:29] op_sel_hi:[0,1,1]
	v_pk_add_f32 v[32:33], v[54:55], v[32:33] op_sel_hi:[0,1]
	v_pk_fma_f32 v[32:33], v[26:27], v[26:27], v[32:33]
	v_mul_f32_e32 v58, v29, v29
	v_pk_add_f32 v[32:33], v[56:57], v[32:33] op_sel_hi:[0,1]
	v_pk_fma_f32 v[32:33], v[28:29], v[28:29], v[32:33]
	v_pk_fma_f32 v[30:31], v[78:79], v[62:63], v[30:31] op_sel_hi:[0,1,1]
	v_pk_add_f32 v[32:33], v[58:59], v[32:33] op_sel_hi:[0,1]
	v_mul_f32_e32 v60, v31, v31
	v_pk_fma_f32 v[32:33], v[30:31], v[30:31], v[32:33]
	v_pk_fma_f32 v[2:3], v[78:79], v[34:35], v[2:3] op_sel_hi:[0,1,1]
	v_pk_add_f32 v[32:33], v[60:61], v[32:33] op_sel_hi:[0,1]
	v_mul_f32_e32 v34, v1, v1
	v_pk_fma_f32 v[32:33], v[0:1], v[0:1], v[32:33]
	v_mul_f32_e32 v46, v3, v3
	v_pk_add_f32 v[32:33], v[34:35], v[32:33] op_sel_hi:[0,1]
	v_pk_fma_f32 v[32:33], v[2:3], v[2:3], v[32:33]
	v_pk_fma_f32 v[4:5], v[78:79], v[36:37], v[4:5] op_sel_hi:[0,1,1]
	v_pk_add_f32 v[32:33], v[46:47], v[32:33] op_sel_hi:[0,1]
	v_pk_fma_f32 v[32:33], v[4:5], v[4:5], v[32:33]
	v_mul_f32_e32 v36, v5, v5
	v_pk_fma_f32 v[6:7], v[78:79], v[38:39], v[6:7] op_sel_hi:[0,1,1]
	v_pk_add_f32 v[32:33], v[36:37], v[32:33] op_sel_hi:[0,1]
	v_pk_fma_f32 v[32:33], v[6:7], v[6:7], v[32:33]
	v_mul_f32_e32 v38, v7, v7
	v_pk_add_f32 v[32:33], v[38:39], v[32:33] op_sel_hi:[0,1]
	v_pk_fma_f32 v[8:9], v[78:79], v[40:41], v[8:9] op_sel_hi:[0,1,1]
	v_pk_fma_f32 v[32:33], v[8:9], v[8:9], v[32:33]
	v_mul_f32_e32 v40, v9, v9
	v_pk_fma_f32 v[10:11], v[78:79], v[42:43], v[10:11] op_sel_hi:[0,1,1]
	v_pk_add_f32 v[32:33], v[40:41], v[32:33] op_sel_hi:[0,1]
	v_pk_fma_f32 v[32:33], v[10:11], v[10:11], v[32:33]
	v_mul_f32_e32 v42, v11, v11
	v_pk_add_f32 v[32:33], v[42:43], v[32:33] op_sel_hi:[0,1]
	v_pk_fma_f32 v[12:13], v[78:79], v[44:45], v[12:13] op_sel_hi:[0,1,1]
	v_pk_fma_f32 v[32:33], v[12:13], v[12:13], v[32:33]
	v_mul_f32_e32 v42, v13, v13
	v_pk_add_f32 v[32:33], v[42:43], v[32:33] op_sel_hi:[0,1]
	v_pk_fma_f32 v[32:33], v[14:15], v[14:15], v[32:33]
	v_mul_f32_e32 v42, v15, v15
	v_pk_add_f32 v[32:33], v[42:43], v[32:33] op_sel_hi:[0,1]
	v_mov_b32_e32 v33, v32
	s_nop 1
	v_permlane32_swap_b32_e32 v32, v33
	v_add_f32_e32 v32, v32, v33
	v_fmamk_f32 v32, v32, 0x3c800000, v189
	v_mul_f32_e32 v33, 0x4b800000, v32
	v_cmp_gt_f32_e32 vcc, s21, v32
	v_lshlrev_b32_e32 v34, 16, v203
	v_and_b32_e32 v35, 0xffff0000, v203
	v_cndmask_b32_e32 v32, v32, v33, vcc
	v_rsq_f32_e32 v42, v32
	v_lshlrev_b32_e32 v36, 16, v204
	v_and_b32_e32 v37, 0xffff0000, v204
	v_lshlrev_b32_e32 v38, 16, v205
	v_mul_f32_e32 v43, 0x45800000, v42
	v_cndmask_b32_e32 v42, v42, v43, vcc
	v_pk_mul_f32 v[16:17], v[16:17], v[42:43] op_sel_hi:[1,0]
	v_pk_mul_f32 v[18:19], v[18:19], v[42:43] op_sel_hi:[1,0]
	v_pk_mul_f32 v[16:17], v[16:17], v[220:221]
	v_pk_mul_f32 v[18:19], v[18:19], v[100:101]
	v_cvt_pk_bf16_f32 v16, v16, v17
	v_cvt_pk_bf16_f32 v17, v18, v19
	v_add_u32_e32 v18, v159, v128
	ds_write_b64 v18, v[16:17]
	v_pk_mul_f32 v[16:17], v[20:21], v[42:43] op_sel_hi:[1,0]
	v_pk_mul_f32 v[18:19], v[22:23], v[42:43] op_sel_hi:[1,0]
	v_pk_mul_f32 v[16:17], v[16:17], v[80:81]
	v_pk_mul_f32 v[18:19], v[18:19], v[82:83]
	v_cvt_pk_bf16_f32 v16, v16, v17
	v_cvt_pk_bf16_f32 v17, v18, v19
	ds_write_b64 v190, v[16:17]
	v_pk_mul_f32 v[16:17], v[24:25], v[42:43] op_sel_hi:[1,0]
	v_pk_mul_f32 v[18:19], v[26:27], v[42:43] op_sel_hi:[1,0]
	v_pk_mul_f32 v[16:17], v[16:17], v[88:89]
	v_pk_mul_f32 v[18:19], v[18:19], v[72:73]
	v_cvt_pk_bf16_f32 v16, v16, v17
	v_cvt_pk_bf16_f32 v17, v18, v19
	ds_write_b64 v191, v[16:17]
	v_pk_mul_f32 v[16:17], v[28:29], v[42:43] op_sel_hi:[1,0]
	v_pk_mul_f32 v[18:19], v[30:31], v[42:43] op_sel_hi:[1,0]
	v_pk_mul_f32 v[0:1], v[0:1], v[42:43] op_sel_hi:[1,0]
	v_pk_mul_f32 v[2:3], v[2:3], v[42:43] op_sel_hi:[1,0]
	v_pk_mul_f32 v[16:17], v[16:17], v[74:75]
	v_pk_mul_f32 v[18:19], v[18:19], v[76:77]
	v_pk_mul_f32 v[0:1], v[0:1], v[218:219]
	v_pk_mul_f32 v[2:3], v[2:3], v[34:35]
	v_cvt_pk_bf16_f32 v16, v16, v17
	v_cvt_pk_bf16_f32 v17, v18, v19
	v_cvt_pk_bf16_f32 v0, v0, v1
	v_cvt_pk_bf16_f32 v1, v2, v3
	v_and_b32_e32 v39, 0xffff0000, v205
	ds_write_b64 v192, v[16:17]
	ds_write_b64 v193, v[0:1]
	v_pk_mul_f32 v[0:1], v[4:5], v[42:43] op_sel_hi:[1,0]
	v_pk_mul_f32 v[2:3], v[6:7], v[42:43] op_sel_hi:[1,0]
	v_pk_mul_f32 v[0:1], v[0:1], v[36:37]
	v_pk_mul_f32 v[2:3], v[2:3], v[38:39]
	v_cvt_pk_bf16_f32 v0, v0, v1
	v_cvt_pk_bf16_f32 v1, v2, v3
	v_lshlrev_b32_e32 v40, 16, v206
	v_and_b32_e32 v41, 0xffff0000, v206
	v_lshlrev_b32_e32 v32, 16, v207
	v_and_b32_e32 v33, 0xffff0000, v207
	ds_write_b64 v194, v[0:1]
	v_pk_mul_f32 v[0:1], v[8:9], v[42:43] op_sel_hi:[1,0]
	v_pk_mul_f32 v[2:3], v[10:11], v[42:43] op_sel_hi:[1,0]
	v_pk_mul_f32 v[0:1], v[0:1], v[40:41]
	v_pk_mul_f32 v[2:3], v[2:3], v[32:33]
	v_cvt_pk_bf16_f32 v0, v0, v1
	v_cvt_pk_bf16_f32 v1, v2, v3
	ds_write_b64 v195, v[0:1]
	v_pk_mul_f32 v[0:1], v[12:13], v[42:43] op_sel_hi:[1,0]
	v_lshlrev_b32_e32 v2, 16, v208
	v_and_b32_e32 v3, 0xffff0000, v208
	v_pk_mul_f32 v[0:1], v[0:1], v[2:3]
	v_pk_mul_f32 v[2:3], v[14:15], v[42:43] op_sel_hi:[1,0]
	v_lshlrev_b32_e32 v4, 16, v209
	v_and_b32_e32 v5, 0xffff0000, v209
	v_pk_mul_f32 v[2:3], v[2:3], v[4:5]
	v_cvt_pk_bf16_f32 v0, v0, v1
	v_cvt_pk_bf16_f32 v1, v2, v3
	ds_write_b64 v196, v[0:1]
	v_mov_b32_e32 v0, v152
	s_nop 0
	v_ashrrev_i32_e32 v1, 31, v0
	v_lshrrev_b32_e32 v1, 29, v1
	v_add_u32_e32 v1, v0, v1
	v_ashrrev_i32_e32 v8, 3, v1
	v_and_b32_e32 v1, -8, v1
	v_sub_u32_e32 v0, v0, v1
	v_bitop3_b32 v1, v8, v0, 7 bitop3:0x6c
	v_lshlrev_b32_e32 v0, 3, v0
	v_lshl_add_u32 v16, v1, 4, s2
	v_ashrrev_i32_e32 v1, 31, v0
	v_lshl_add_u64 v[10:11], v[0:1], 1, s[0:1]
	v_lshl_add_u32 v0, v8, 7, v16
	v_ashrrev_i32_e32 v9, 31, v8
	ds_read_b128 v[0:3], v0
	v_lshlrev_b64 v[4:5], 11, v[8:9]
	v_add_u32_e32 v14, 8, v8
	v_lshl_add_u64 v[12:13], v[10:11], 0, v[4:5]
	v_lshl_add_u32 v4, v14, 7, v16
	ds_read_b128 v[4:7], v4
	v_ashrrev_i32_e32 v15, 31, v14
	s_waitcnt lgkmcnt(1)
	global_store_dwordx4 v[12:13], v[0:3], off
	s_nop 1
	v_lshlrev_b64 v[0:1], 11, v[14:15]
	v_lshl_add_u64 v[0:1], v[10:11], 0, v[0:1]
	s_waitcnt lgkmcnt(0)
	global_store_dwordx4 v[0:1], v[4:7], off
	s_nop 1
	v_add_u32_e32 v4, 16, v8
	v_lshl_add_u32 v0, v4, 7, v16
	v_ashrrev_i32_e32 v5, 31, v4
	ds_read_b128 v[0:3], v0
	v_lshlrev_b64 v[4:5], 11, v[4:5]
	v_add_u32_e32 v8, 24, v8
	v_lshl_add_u64 v[12:13], v[10:11], 0, v[4:5]
	v_lshl_add_u32 v4, v8, 7, v16
	ds_read_b128 v[4:7], v4
	v_ashrrev_i32_e32 v9, 31, v8
	s_waitcnt lgkmcnt(1)
	global_store_dwordx4 v[12:13], v[0:3], off
	s_nop 1
	v_lshlrev_b64 v[0:1], 11, v[8:9]
	v_lshl_add_u64 v[0:1], v[10:11], 0, v[0:1]
	s_waitcnt lgkmcnt(0)
	global_store_dwordx4 v[0:1], v[4:7], off
	s_cbranch_scc0 .LBB0_594
	v_readlane_b32 s66, v254, 22
	v_readlane_b32 s67, v254, 23

.LBB0_634:
	s_andn2_saveexec_b64 s[2:3], s[8:9]
	s_cbranch_execz .LBB0_654
	s_mov_b64 s[8:9], exec
	s_cmp_lg_u32 s98, 0
	s_cbranch_scc0 .Lxl_full_5
	s_mov_b64 s[8:9], exec
	buffer_wbl2 sc1
	s_waitcnt vmcnt(0)
	v_mov_b32_e32 v14, 0xfa03a00
	v_mov_b32_e32 v15, 1
	global_atomic_add v14, v15, s[74:75]
	buffer_inv sc1
	s_branch .LBB0_651

.Lgp_done_g752:
	v_mov_b32_e32 v0, 0x21004
	ds_read_b32 v1, v0
	v_mov_b32_e32 v0, 0xfa03a00
	s_mov_b32 s99, 0
	s_waitcnt lgkmcnt(0)

.LBB0_831:
	s_cmp_lg_u32 s98, 0
	s_cbranch_scc0 .Lk7_nowait
	v_readlane_b32 s99, v254, 25
	s_nop 3
	s_cmp_lg_u32 s99, 0
	s_cbranch_scc1 .Lk7_nowait
	s_mov_b64 s[100:101], exec
	s_mov_b64 exec, 1
	v_mov_b32_e32 v0, 0x21004
	ds_read_b32 v1, v0
	v_mov_b32_e32 v0, 0xfa03a00
	s_mov_b32 s99, 0
	s_waitcnt lgkmcnt(0)

.Lk7_done:
	buffer_inv sc1
	s_waitcnt vmcnt(0)
	s_mov_b64 exec, s[100:101]
.Lk7_nowait:
	v_mbcnt_lo_u32_b32 v199, -1, 0
	v_mbcnt_hi_u32_b32 v199, -1, v199
	v_lshlrev_b32_e32 v199, 2, v199
	v_readlane_b32 s100, v254, 40
	v_readlane_b32 s101, v254, 41
	s_nop 4
	global_load_dword v200, v199, s[100:101]
	global_load_dword v201, v199, s[100:101] offset:256
	global_load_dword v202, v199, s[100:101] offset:512
	global_load_dword v203, v199, s[100:101] offset:768
	v_readlane_b32 s100, v254, 42
	v_readlane_b32 s101, v254, 43
	s_nop 4
	global_load_dword v204, v199, s[100:101]
	global_load_dword v205, v199, s[100:101] offset:256
	global_load_dword v206, v199, s[100:101] offset:512
	global_load_dword v207, v199, s[100:101] offset:768
	v_readlane_b32 s8, v254, 28
	s_waitcnt lgkmcnt(0)
	s_barrier
	v_mbcnt_lo_u32_b32 v144, -1, 0
	v_mbcnt_hi_u32_b32 v144, -1, v144
	v_readlane_b32 s16, v254, 36
	v_ashrrev_i32_e32 v145, 31, v144
	v_readlane_b32 s17, v254, 37
	v_readlane_b32 s18, v254, 38
	v_readlane_b32 s19, v254, 39
	v_readlane_b32 s20, v254, 40
	v_readlane_b32 s21, v254, 41
	v_lshlrev_b64 v[0:1], 2, v[144:145]
	v_readlane_b32 s22, v254, 42
	v_readlane_b32 s23, v254, 43
	s_mov_b64 s[16:17], s[20:21]
	s_mov_b64 s[18:19], s[22:23]
	v_lshl_add_u64 v[2:3], s[16:17], 0, v[0:1]
	v_lshl_add_u64 v[0:1], s[18:19], 0, v[0:1]
	s_waitcnt vmcnt(0)
	v_mov_b32_e32 v4, v200
	v_mov_b32_e32 v5, v201
	v_mov_b32_e32 v6, v202
	v_mov_b32_e32 v7, v203
	v_mov_b32_e32 v8, v204
	v_mov_b32_e32 v9, v205
	v_mov_b32_e32 v10, v206
	v_mov_b32_e32 v11, v207
	s_add_u32 s2, s74, 0x6600000
	s_mov_b32 s1, 0
	s_addc_u32 s3, s75, 0
	s_and_b64 vcc, exec, s[4:5]
	v_readlane_b32 s9, v254, 29
	v_readlane_b32 s10, v254, 30
	v_readlane_b32 s11, v254, 31
	v_readlane_b32 s12, v254, 32
	v_readlane_b32 s13, v254, 33
	v_readlane_b32 s14, v254, 34
	v_readlane_b32 s15, v254, 35
	s_waitcnt vmcnt(0)
	v_max3_f32 v0, |v4|, 0, |v5|
	v_mov_b32_e32 v4, 0xc2700000
	v_max3_f32 v0, v0, |v6|, |v7|
	ds_swizzle_b32 v2, v0 offset:swizzle(SWAP,1)
	v_max3_f32 v1, |v8|, 0, |v9|
	v_max3_f32 v1, v1, |v10|, |v11|
	ds_swizzle_b32 v3, v1 offset:swizzle(SWAP,1)
	s_waitcnt lgkmcnt(1)
	v_max_f32_e32 v2, v2, v2
	v_max_f32_e32 v0, v0, v2
	ds_swizzle_b32 v2, v0 offset:swizzle(SWAP,2)
	s_waitcnt lgkmcnt(1)
	v_max_f32_e32 v3, v3, v3
	v_max_f32_e32 v1, v1, v3
	ds_swizzle_b32 v3, v1 offset:swizzle(SWAP,2)
	s_waitcnt lgkmcnt(1)
	v_max_f32_e32 v2, v2, v2
	v_max_f32_e32 v0, v0, v2
	ds_swizzle_b32 v2, v0 offset:swizzle(SWAP,4)
	s_waitcnt lgkmcnt(1)
	v_max_f32_e32 v3, v3, v3
	v_max_f32_e32 v1, v1, v3
	ds_swizzle_b32 v3, v1 offset:swizzle(SWAP,4)
	s_waitcnt lgkmcnt(1)
	v_max_f32_e32 v2, v2, v2
	v_max_f32_e32 v0, v0, v2
	ds_swizzle_b32 v2, v0 offset:swizzle(SWAP,8)
	s_waitcnt lgkmcnt(1)
	v_max_f32_e32 v3, v3, v3
	v_max_f32_e32 v1, v1, v3
	ds_swizzle_b32 v3, v1 offset:swizzle(SWAP,8)
	s_waitcnt lgkmcnt(1)
	v_max_f32_e32 v2, v2, v2
	v_max_f32_e32 v0, v0, v2
	ds_swizzle_b32 v2, v0 offset:swizzle(SWAP,16)
	s_waitcnt lgkmcnt(1)
	v_max_f32_e32 v3, v3, v3
	v_max_f32_e32 v1, v1, v3
	ds_swizzle_b32 v3, v1 offset:swizzle(SWAP,16)
	s_waitcnt lgkmcnt(1)
	v_max_f32_e32 v2, v2, v2
	v_max_f32_e32 v0, v0, v2
	v_mov_b32_e32 v2, v0
	s_nop 1
	v_permlane32_swap_b32_e32 v0, v2
	s_waitcnt lgkmcnt(0)
	v_max_f32_e32 v3, v3, v3
	v_max_f32_e32 v1, v1, v3
	v_mov_b32_e32 v3, v1
	s_nop 1
	v_permlane32_swap_b32_e32 v1, v3
	v_max_f32_e32 v2, v2, v2
	v_max_f32_e32 v0, v0, v0
	v_max_f32_e32 v3, v3, v3
	v_max_f32_e32 v1, v1, v1
	v_max_f32_e32 v0, v0, v2
	v_max_f32_e32 v1, v1, v3
	v_mul_f32_e32 v0, v0, v1
	v_mul_f32_e32 v0, 0x43800000, v0
	v_fmac_f32_e32 v4, 0x3db8aa3b, v0
	v_max_f32_e32 v0, 0, v4
	s_nop 0
	v_readfirstlane_b32 s7, v0
	s_cbranch_vccnz .LBB0_844
	v_readlane_b32 s0, v254, 44
	v_and_b32_e32 v4, 7, v144
	v_readlane_b32 s4, v254, 45
	v_add_u32_e32 v2, s0, v144
	v_lshlrev_b32_e32 v3, 2, v144
	s_add_i32 s0, 0, 0x20000
	v_mov_b32_e32 v149, 0
	v_lshlrev_b32_e32 v148, 4, v4
	v_readlane_b32 s5, v254, 46
	v_readlane_b32 s8, v254, 52
	v_and_b32_e32 v1, 31, v144
	v_add_u32_e32 v161, s0, v3
	v_lshl_add_u64 v[150:151], s[4:5], 0, v[148:149]
	s_add_i32 s0, 0, 0x10000
	s_lshl_b32 s4, s8, 14
	s_add_i32 s4, s0, s4
	v_lshlrev_b32_e32 v7, 9, v1
	v_add_u32_e32 v166, s4, v7
	v_lshlrev_b32_e32 v9, 4, v144
	s_movk_i32 s4, 0x70
	v_ashrrev_i32_e32 v146, 3, v2
	v_bitop3_b32 v2, v2, s4, v9 bitop3:0x48
	v_and_b32_e32 v9, 19, v144
	v_lshlrev_b32_e32 v10, 1, v144
	v_lshrrev_b32_e32 v11, 1, v144
	v_readlane_b32 s5, v254, 48
	v_and_b32_e32 v10, 8, v10
	v_and_or_b32 v9, v11, 4, v9
	s_lshl_b32 s4, s5, 14
	v_or_b32_e32 v12, v9, v10
	s_add_i32 s4, s4, 0
	v_readlane_b32 s6, v254, 25
	v_ashrrev_i32_e32 v145, 5, v144
	v_lshl_add_u32 v168, v12, 9, s4
	s_and_b32 s4, s6, 0x3fffffc
	v_bitop3_b32 v169, v9, 15, v10 bitop3:0xc8
	v_add_u32_e32 v9, s4, v145
	s_lshl_b32 s4, s8, 15
	s_add_i32 s11, s4, 0
	v_lshlrev_b32_e32 v5, 9, v146
	v_add_u32_e32 v171, s11, v3
	v_lshlrev_b32_e32 v3, 3, v145
	v_and_b32_e32 v6, 0x3e00, v5
	v_add3_u32 v172, s11, v7, v3
	v_and_b32_e32 v3, 0xffffc000, v5
	v_add3_u32 v173, s0, v6, v3
	v_bitop3_b32 v3, v146, v4, 15 bitop3:0x6c
	v_lshlrev_b32_e32 v148, 5, v4
	v_lshlrev_b32_e32 v174, 4, v3
	v_or_b32_e32 v3, 8, v4
	v_lshl_add_u64 v[152:153], s[16:17], 0, v[148:149]
	v_lshlrev_b32_e32 v148, 5, v3
	v_bitop3_b32 v3, v146, v3, 15 bitop3:0x6c
	v_lshlrev_b32_e32 v175, 4, v3
	v_or_b32_e32 v3, 16, v4
	v_lshl_add_u64 v[154:155], s[16:17], 0, v[148:149]
	v_lshlrev_b32_e32 v148, 5, v3
	v_bitop3_b32 v3, v146, v3, 15 bitop3:0x6c
	v_lshlrev_b32_e32 v176, 4, v3
	v_or_b32_e32 v3, 24, v4
	v_lshlrev_b32_e32 v0, 3, v4
	v_lshl_add_u64 v[156:157], s[16:17], 0, v[148:149]
	v_lshlrev_b32_e32 v148, 5, v3
	v_bitop3_b32 v3, v146, v3, 15 bitop3:0x6c
	v_add_u32_e32 v4, 2, v9
	v_lshlrev_b32_e32 v177, 4, v3
	v_bitop3_b32 v3, v9, v11, 7 bitop3:0x78
	v_bitop3_b32 v4, v4, v11, 7 bitop3:0x78
	v_lshlrev_b32_e32 v178, 4, v1
	v_add_u32_e32 v167, 0, v5
	v_lshl_add_u32 v8, v146, 7, 0
	v_lshl_add_u32 v10, v1, 7, 0
	s_cmp_eq_u32 s5, 1
	v_lshlrev_b32_e32 v3, 4, v3
	v_lshlrev_b32_e32 v4, 4, v4
	v_xor_b32_e32 v1, 16, v178
	v_xor_b32_e32 v5, 32, v178
	v_xor_b32_e32 v6, 48, v178
	v_xor_b32_e32 v7, 64, v178
	v_xor_b32_e32 v9, 0x50, v178
	v_xor_b32_e32 v11, 0x60, v178
	v_xor_b32_e32 v12, 0x70, v178
	v_xor_b32_e32 v13, 0x80, v178
	v_xor_b32_e32 v14, 0x90, v178
	v_xor_b32_e32 v15, 0xa0, v178
	v_xor_b32_e32 v16, 0xb0, v178
	v_xor_b32_e32 v17, 0xc0, v178
	v_xor_b32_e32 v18, 0xd0, v178
	v_xor_b32_e32 v19, 0xe0, v178
	v_xor_b32_e32 v20, 0xf0, v178
	v_xor_b32_e32 v21, 0x100, v178
	v_xor_b32_e32 v22, 0x110, v178
	v_xor_b32_e32 v23, 0x120, v178
	v_xor_b32_e32 v24, 0x130, v178
	v_xor_b32_e32 v25, 0x140, v178
	v_xor_b32_e32 v26, 0x150, v178
	v_xor_b32_e32 v27, 0x160, v178
	v_xor_b32_e32 v28, 0x170, v178
	v_xor_b32_e32 v29, 0x180, v178
	v_xor_b32_e32 v30, 0x190, v178
	v_xor_b32_e32 v31, 0x1a0, v178
	v_xor_b32_e32 v32, 0x1b0, v178
	v_xor_b32_e32 v33, 0x1c0, v178
	v_xor_b32_e32 v34, 0x1d0, v178
	v_xor_b32_e32 v35, 0x1e0, v178
	v_xor_b32_e32 v36, 0x1f0, v178
	s_mov_b32 s10, 0x20000
	v_ashrrev_i32_e32 v147, 31, v146
	v_and_b32_e32 v170, 15, v144
	s_cselect_b64 s[4:5], -1, 0
	s_lshl_b32 s12, s8, 8
	s_lshl_b32 s13, s6, 8
	v_lshl_add_u64 v[158:159], s[16:17], 0, v[148:149]
	s_mov_b32 s6, 0x3b800000
	s_mov_b32 s14, 0x800000
	v_lshlrev_b32_e32 v148, 1, v0
	v_add_u32_e32 v179, v8, v2
	v_add_u32_e32 v180, v10, v3
	v_add_u32_e32 v181, v10, v4
	v_add_u32_e32 v182, v172, v1
	v_add_u32_e32 v183, v172, v5
	v_add_u32_e32 v184, v172, v6
	v_add_u32_e32 v185, v172, v7
	v_add_u32_e32 v186, v172, v9
	v_add_u32_e32 v187, v172, v11
	v_add_u32_e32 v188, v172, v12
	v_add_u32_e32 v189, v172, v13
	v_add_u32_e32 v190, v172, v14
	v_add_u32_e32 v191, v172, v15
	v_add_u32_e32 v192, v172, v16
	v_add_u32_e32 v193, v172, v17
	v_add_u32_e32 v194, v172, v18
	v_add_u32_e32 v195, v172, v19
	v_add_u32_e32 v196, v172, v20
	v_add_u32_e32 v197, v172, v21
	v_add_u32_e32 v198, v172, v22
	v_add_u32_e32 v199, v172, v23
	v_add_u32_e32 v200, v172, v24
	v_add_u32_e32 v201, v172, v25
	v_add_u32_e32 v202, v172, v26
	v_add_u32_e32 v203, v172, v27
	v_add_u32_e32 v204, v172, v28
	v_add_u32_e32 v205, v172, v29
	v_add_u32_e32 v206, v172, v30
	v_add_u32_e32 v207, v172, v31
	v_add_u32_e32 v208, v172, v32
	v_add_u32_e32 v209, v172, v33
	v_add_u32_e32 v210, v172, v34
	v_add_u32_e32 v211, v172, v35
	v_add_u32_e32 v212, v172, v36
	v_mov_b32_e32 v160, 0x358637bd
	s_mov_b32 s15, s70
	s_cmp_eq_u32 s78, 0x100
	s_cbranch_scc0 .LBB0_834
	s_and_b32 s15, s70, 7
	s_lshr_b32 s16, s15, 2
	s_lshl_b32 s16, s16, 8
	s_and_b32 s15, s15, 3
	s_lshl_b32 s15, s15, 4
	s_or_b32 s15, s15, s16
	s_lshr_b32 s16, s70, 3
	s_and_b32 s16, s16, 7
	s_lshl_b32 s16, s16, 1
	s_or_b32 s15, s15, s16
	s_lshr_b32 s16, s70, 6
	s_lshl_b32 s16, s16, 6
	s_or_b32 s15, s15, s16
	s_branch .LBB0_834
